# v011_fullline
# speedup vs baseline: 1.0201x; 1.0201x over previous
; __device__ __forceinline__ void convert_item(const float* __restrict__ src, int Ksz, int Nsz, u16* __restrict__ dst, int kb, int nb,
;                                              int mode, const int tid) {
;   const int n = nb * NTHR + tid;
;   if (n < Nsz) {
;     const float* sp = src + (size_t)(kb * 64) * Nsz + n;
;     float v[64];
; #pragma unroll
;     for (int j = 0; j < 64; ++j) v[j] = sp[(size_t)j * Nsz];
;     int nd = n;
;     if (mode == 1) {
;       int isg = n >= 1024, c = n & 1023;
;       nd = (c >> 7) * 256 + isg * 128 + (c & 127);
;     }
;     u32x4* d = reinterpret_cast<u32x4*>(dst + (size_t)nd * Ksz + kb * 64);
; #pragma unroll
;     for (int q = 0; q < 8; ++q) {
;       u32x4 o;
;       o.x = pack2(v[q * 8 + 0], v[q * 8 + 1]);
;       o.y = pack2(v[q * 8 + 2], v[q * 8 + 3]);
;       o.z = pack2(v[q * 8 + 4], v[q * 8 + 5]);
;       o.w = pack2(v[q * 8 + 6], v[q * 8 + 7]);
;       d[q] = o;
;     }
.Lcvm_common:
	s_lshl_b32 s29, s29, 8
	s_mul_i32 s30, s29, s24
	s_lshl_b32 s31, s28, 9
	s_add_u32 s30, s30, s31
	s_lshl_b32 s30, s30, 2
	s_add_u32 s8, s8, s30
	s_addc_u32 s9, s9, 0
	s_lshl_b32 s10, s24, 2
	v_add_u32_e32 v84, s31, v164
	v_cmp_gt_u32_e32 vcc, s24, v84
	s_and_b64 exec, exec, vcc
	s_cbranch_execz .Lcvm_done
	v_and_b32_e32 v85, 63, v164
	v_sub_u32_e32 v84, v84, v85
	v_lshrrev_b32_e32 v85, 3, v85
	v_add_u32_e32 v84, v84, v85
	s_cmp_eq_u32 s27, 0
	s_cbranch_scc1 .Lcvm_nd
	v_and_b32_e32 v85, 0x3ff, v84
	v_lshrrev_b32_e32 v86, 7, v85
	v_lshlrev_b32_e32 v86, 8, v86
	v_and_b32_e32 v85, 0x7f, v85
	v_lshrrev_b32_e32 v87, 3, v84
	v_and_b32_e32 v87, 0x80, v87
	v_or3_b32 v84, v86, v85, v87
.Lcvm_nd:
	s_lshl_b32 s30, s25, 1
	s_lshl_b32 s31, s29, 1
	s_add_u32 s22, s22, s31
	s_addc_u32 s23, s23, 0
	s_lshl_b32 s6, s30, 3
	s_mov_b32 s7, 0
	v_mov_b32_e32 v86, s22
	v_mov_b32_e32 v87, s23
	v_mov_b32_e32 v88, s30
	v_mad_u64_u32 v[90:91], vcc, v84, v88, v[86:87]
	v_and_b32_e32 v0, 7, v164
	v_lshlrev_b32_e32 v0, 4, v0
	v_add_co_u32_e32 v84, vcc, v90, v0
	s_nop 1
	v_addc_co_u32_e32 v85, vcc, 0, v91, vcc
	v_lshlrev_b32_e32 v1, 2, v164
	v_lshrrev_b32_e32 v2, 6, v164
	v_mul_u32_u24_e32 v2, 0x2400, v2
	v_and_b32_e32 v3, 63, v164
	v_lshrrev_b32_e32 v89, 3, v3
	v_mul_u32_u24_e32 v89, 0x90, v89
	v_add3_u32 v89, v89, v0, v2
	v_mul_u32_u24_e32 v3, 0x90, v3
	v_add3_u32 v2, v2, v3, 32
	v_add_u32_e32 v3, 32, v89
	global_load_dword v4, v1, s[8:9]
	s_add_u32 s8, s8, s10
	s_addc_u32 s9, s9, 0
	global_load_dword v5, v1, s[8:9]
	s_add_u32 s8, s8, s10
	s_addc_u32 s9, s9, 0
	global_load_dword v6, v1, s[8:9]
	s_add_u32 s8, s8, s10
	s_addc_u32 s9, s9, 0
	global_load_dword v7, v1, s[8:9]
	s_add_u32 s8, s8, s10
	s_addc_u32 s9, s9, 0
	global_load_dword v8, v1, s[8:9]
	s_add_u32 s8, s8, s10
	s_addc_u32 s9, s9, 0
	global_load_dword v9, v1, s[8:9]
	s_add_u32 s8, s8, s10
	s_addc_u32 s9, s9, 0
	global_load_dword v10, v1, s[8:9]
	s_add_u32 s8, s8, s10
	s_addc_u32 s9, s9, 0
	global_load_dword v11, v1, s[8:9]
	s_add_u32 s8, s8, s10
	s_addc_u32 s9, s9, 0
	global_load_dword v12, v1, s[8:9]
	s_add_u32 s8, s8, s10
	s_addc_u32 s9, s9, 0
	global_load_dword v13, v1, s[8:9]
	s_add_u32 s8, s8, s10
	s_addc_u32 s9, s9, 0
	global_load_dword v14, v1, s[8:9]
	s_add_u32 s8, s8, s10
	s_addc_u32 s9, s9, 0
	global_load_dword v15, v1, s[8:9]
	s_add_u32 s8, s8, s10
	s_addc_u32 s9, s9, 0
	global_load_dword v16, v1, s[8:9]
	s_add_u32 s8, s8, s10
	s_addc_u32 s9, s9, 0
	global_load_dword v17, v1, s[8:9]
	s_add_u32 s8, s8, s10
	s_addc_u32 s9, s9, 0
	global_load_dword v18, v1, s[8:9]
	s_add_u32 s8, s8, s10
	s_addc_u32 s9, s9, 0
	global_load_dword v19, v1, s[8:9]
	s_add_u32 s8, s8, s10
	s_addc_u32 s9, s9, 0
	global_load_dword v20, v1, s[8:9]
	s_add_u32 s8, s8, s10
	s_addc_u32 s9, s9, 0
	global_load_dword v21, v1, s[8:9]
	s_add_u32 s8, s8, s10
	s_addc_u32 s9, s9, 0
	global_load_dword v22, v1, s[8:9]
	s_add_u32 s8, s8, s10
	s_addc_u32 s9, s9, 0
	global_load_dword v23, v1, s[8:9]
	s_add_u32 s8, s8, s10
	s_addc_u32 s9, s9, 0
	global_load_dword v24, v1, s[8:9]
	s_add_u32 s8, s8, s10
	s_addc_u32 s9, s9, 0
	global_load_dword v25, v1, s[8:9]
	s_add_u32 s8, s8, s10
	s_addc_u32 s9, s9, 0
	global_load_dword v26, v1, s[8:9]
	s_add_u32 s8, s8, s10
	s_addc_u32 s9, s9, 0
	global_load_dword v27, v1, s[8:9]
	s_add_u32 s8, s8, s10
	s_addc_u32 s9, s9, 0
	global_load_dword v28, v1, s[8:9]
	s_add_u32 s8, s8, s10
	s_addc_u32 s9, s9, 0
	global_load_dword v29, v1, s[8:9]
	s_add_u32 s8, s8, s10
	s_addc_u32 s9, s9, 0
	global_load_dword v30, v1, s[8:9]
	s_add_u32 s8, s8, s10
	s_addc_u32 s9, s9, 0
	global_load_dword v31, v1, s[8:9]
	s_add_u32 s8, s8, s10
	s_addc_u32 s9, s9, 0
	global_load_dword v32, v1, s[8:9]
	s_add_u32 s8, s8, s10
	s_addc_u32 s9, s9, 0
	global_load_dword v33, v1, s[8:9]
	s_add_u32 s8, s8, s10
	s_addc_u32 s9, s9, 0
	global_load_dword v34, v1, s[8:9]
	s_add_u32 s8, s8, s10
	s_addc_u32 s9, s9, 0
	global_load_dword v35, v1, s[8:9]
	s_add_u32 s8, s8, s10
	s_addc_u32 s9, s9, 0
	global_load_dword v36, v1, s[8:9]
	s_add_u32 s8, s8, s10
	s_addc_u32 s9, s9, 0
	global_load_dword v37, v1, s[8:9]
	s_add_u32 s8, s8, s10
	s_addc_u32 s9, s9, 0
	global_load_dword v38, v1, s[8:9]
	s_add_u32 s8, s8, s10
	s_addc_u32 s9, s9, 0
	global_load_dword v39, v1, s[8:9]
	s_add_u32 s8, s8, s10
	s_addc_u32 s9, s9, 0
	global_load_dword v40, v1, s[8:9]
	s_add_u32 s8, s8, s10
	s_addc_u32 s9, s9, 0
	global_load_dword v41, v1, s[8:9]
	s_add_u32 s8, s8, s10
	s_addc_u32 s9, s9, 0
	global_load_dword v42, v1, s[8:9]
	s_add_u32 s8, s8, s10
	s_addc_u32 s9, s9, 0
	global_load_dword v43, v1, s[8:9]
	s_add_u32 s8, s8, s10
	s_addc_u32 s9, s9, 0
	global_load_dword v44, v1, s[8:9]
	s_add_u32 s8, s8, s10
	s_addc_u32 s9, s9, 0
	global_load_dword v45, v1, s[8:9]
	s_add_u32 s8, s8, s10
	s_addc_u32 s9, s9, 0
	global_load_dword v46, v1, s[8:9]
	s_add_u32 s8, s8, s10
	s_addc_u32 s9, s9, 0
	global_load_dword v47, v1, s[8:9]
	s_add_u32 s8, s8, s10
	s_addc_u32 s9, s9, 0
	global_load_dword v48, v1, s[8:9]
	s_add_u32 s8, s8, s10
	s_addc_u32 s9, s9, 0
	global_load_dword v49, v1, s[8:9]
	s_add_u32 s8, s8, s10
	s_addc_u32 s9, s9, 0
	global_load_dword v50, v1, s[8:9]
	s_add_u32 s8, s8, s10
	s_addc_u32 s9, s9, 0
	global_load_dword v51, v1, s[8:9]
	s_add_u32 s8, s8, s10
	s_addc_u32 s9, s9, 0
	global_load_dword v52, v1, s[8:9]
	s_add_u32 s8, s8, s10
	s_addc_u32 s9, s9, 0
	global_load_dword v53, v1, s[8:9]
	s_add_u32 s8, s8, s10
	s_addc_u32 s9, s9, 0
	global_load_dword v54, v1, s[8:9]
	s_add_u32 s8, s8, s10
	s_addc_u32 s9, s9, 0
	global_load_dword v55, v1, s[8:9]
	s_add_u32 s8, s8, s10
	s_addc_u32 s9, s9, 0
	global_load_dword v56, v1, s[8:9]
	s_add_u32 s8, s8, s10
	s_addc_u32 s9, s9, 0
	global_load_dword v57, v1, s[8:9]
	s_add_u32 s8, s8, s10
	s_addc_u32 s9, s9, 0
	global_load_dword v58, v1, s[8:9]
	s_add_u32 s8, s8, s10
	s_addc_u32 s9, s9, 0
	global_load_dword v59, v1, s[8:9]
	s_add_u32 s8, s8, s10
	s_addc_u32 s9, s9, 0
	global_load_dword v60, v1, s[8:9]
	s_add_u32 s8, s8, s10
	s_addc_u32 s9, s9, 0
	global_load_dword v61, v1, s[8:9]
	s_add_u32 s8, s8, s10
	s_addc_u32 s9, s9, 0
	global_load_dword v62, v1, s[8:9]
	s_add_u32 s8, s8, s10
	s_addc_u32 s9, s9, 0
	global_load_dword v63, v1, s[8:9]
	s_add_u32 s8, s8, s10
	s_addc_u32 s9, s9, 0
	global_load_dword v64, v1, s[8:9]
	s_add_u32 s8, s8, s10
	s_addc_u32 s9, s9, 0
	global_load_dword v65, v1, s[8:9]
	s_add_u32 s8, s8, s10
	s_addc_u32 s9, s9, 0
	global_load_dword v66, v1, s[8:9]
	s_add_u32 s8, s8, s10
	s_addc_u32 s9, s9, 0
	global_load_dword v67, v1, s[8:9]
	s_add_u32 s8, s8, s10
	s_addc_u32 s9, s9, 0
	s_waitcnt vmcnt(32)
; __device__ __forceinline__ void convert_item(const float* __restrict__ src, int Ksz, int Nsz, u16* __restrict__ dst, int kb, int nb,
;                                              int mode, const int tid) {
;     ...
; #pragma unroll
;     for (int q = 0; q < 8; ++q) {
;       u32x4 o;
;       o.x = pack2(v[q * 8 + 0], v[q * 8 + 1]);
;       o.y = pack2(v[q * 8 + 2], v[q * 8 + 3]);
;       o.z = pack2(v[q * 8 + 4], v[q * 8 + 5]);
;       o.w = pack2(v[q * 8 + 6], v[q * 8 + 7]);
;       d[q] = o;
;     }
	v_cvt_pk_bf16_f32 v68, v4, v5
	v_cvt_pk_bf16_f32 v69, v6, v7
	v_cvt_pk_bf16_f32 v70, v8, v9
	v_cvt_pk_bf16_f32 v71, v10, v11
	v_cvt_pk_bf16_f32 v72, v12, v13
	v_cvt_pk_bf16_f32 v73, v14, v15
	v_cvt_pk_bf16_f32 v74, v16, v17
	v_cvt_pk_bf16_f32 v75, v18, v19
	v_cvt_pk_bf16_f32 v76, v20, v21
	v_cvt_pk_bf16_f32 v77, v22, v23
	v_cvt_pk_bf16_f32 v78, v24, v25
	v_cvt_pk_bf16_f32 v79, v26, v27
	v_cvt_pk_bf16_f32 v80, v28, v29
	v_cvt_pk_bf16_f32 v81, v30, v31
	v_cvt_pk_bf16_f32 v82, v32, v33
	v_cvt_pk_bf16_f32 v83, v34, v35
	ds_write_b128 v2, v[68:71] offset:0
	ds_write_b128 v2, v[72:75] offset:16
	ds_write_b128 v2, v[76:79] offset:32
	ds_write_b128 v2, v[80:83] offset:48
	global_load_dword v4, v1, s[8:9]
	s_add_u32 s8, s8, s10
	s_addc_u32 s9, s9, 0
	global_load_dword v5, v1, s[8:9]
	s_add_u32 s8, s8, s10
	s_addc_u32 s9, s9, 0
	global_load_dword v6, v1, s[8:9]
	s_add_u32 s8, s8, s10
	s_addc_u32 s9, s9, 0
	global_load_dword v7, v1, s[8:9]
	s_add_u32 s8, s8, s10
	s_addc_u32 s9, s9, 0
	global_load_dword v8, v1, s[8:9]
	s_add_u32 s8, s8, s10
	s_addc_u32 s9, s9, 0
	global_load_dword v9, v1, s[8:9]
	s_add_u32 s8, s8, s10
	s_addc_u32 s9, s9, 0
	global_load_dword v10, v1, s[8:9]
	s_add_u32 s8, s8, s10
	s_addc_u32 s9, s9, 0
	global_load_dword v11, v1, s[8:9]
	s_add_u32 s8, s8, s10
	s_addc_u32 s9, s9, 0
	global_load_dword v12, v1, s[8:9]
	s_add_u32 s8, s8, s10
	s_addc_u32 s9, s9, 0
	global_load_dword v13, v1, s[8:9]
	s_add_u32 s8, s8, s10
	s_addc_u32 s9, s9, 0
	global_load_dword v14, v1, s[8:9]
	s_add_u32 s8, s8, s10
	s_addc_u32 s9, s9, 0
	global_load_dword v15, v1, s[8:9]
	s_add_u32 s8, s8, s10
	s_addc_u32 s9, s9, 0
	global_load_dword v16, v1, s[8:9]
	s_add_u32 s8, s8, s10
	s_addc_u32 s9, s9, 0
	global_load_dword v17, v1, s[8:9]
	s_add_u32 s8, s8, s10
	s_addc_u32 s9, s9, 0
	global_load_dword v18, v1, s[8:9]
	s_add_u32 s8, s8, s10
	s_addc_u32 s9, s9, 0
	global_load_dword v19, v1, s[8:9]
	s_add_u32 s8, s8, s10
	s_addc_u32 s9, s9, 0
	global_load_dword v20, v1, s[8:9]
	s_add_u32 s8, s8, s10
	s_addc_u32 s9, s9, 0
	global_load_dword v21, v1, s[8:9]
	s_add_u32 s8, s8, s10
	s_addc_u32 s9, s9, 0
	global_load_dword v22, v1, s[8:9]
	s_add_u32 s8, s8, s10
	s_addc_u32 s9, s9, 0
	global_load_dword v23, v1, s[8:9]
	s_add_u32 s8, s8, s10
	s_addc_u32 s9, s9, 0
	global_load_dword v24, v1, s[8:9]
	s_add_u32 s8, s8, s10
	s_addc_u32 s9, s9, 0
	global_load_dword v25, v1, s[8:9]
	s_add_u32 s8, s8, s10
	s_addc_u32 s9, s9, 0
	global_load_dword v26, v1, s[8:9]
	s_add_u32 s8, s8, s10
	s_addc_u32 s9, s9, 0
	global_load_dword v27, v1, s[8:9]
	s_add_u32 s8, s8, s10
	s_addc_u32 s9, s9, 0
	global_load_dword v28, v1, s[8:9]
	s_add_u32 s8, s8, s10
	s_addc_u32 s9, s9, 0
	global_load_dword v29, v1, s[8:9]
	s_add_u32 s8, s8, s10
	s_addc_u32 s9, s9, 0
	global_load_dword v30, v1, s[8:9]
	s_add_u32 s8, s8, s10
	s_addc_u32 s9, s9, 0
	global_load_dword v31, v1, s[8:9]
	s_add_u32 s8, s8, s10
	s_addc_u32 s9, s9, 0
	global_load_dword v32, v1, s[8:9]
	s_add_u32 s8, s8, s10
	s_addc_u32 s9, s9, 0
	global_load_dword v33, v1, s[8:9]
	s_add_u32 s8, s8, s10
	s_addc_u32 s9, s9, 0
	global_load_dword v34, v1, s[8:9]
	s_add_u32 s8, s8, s10
	s_addc_u32 s9, s9, 0
	global_load_dword v35, v1, s[8:9]
	s_add_u32 s8, s8, s10
	s_addc_u32 s9, s9, 0
	s_waitcnt vmcnt(32)
	v_cvt_pk_bf16_f32 v100, v36, v37
	v_cvt_pk_bf16_f32 v101, v38, v39
	v_cvt_pk_bf16_f32 v102, v40, v41
	v_cvt_pk_bf16_f32 v103, v42, v43
	v_cvt_pk_bf16_f32 v104, v44, v45
	v_cvt_pk_bf16_f32 v105, v46, v47
	v_cvt_pk_bf16_f32 v106, v48, v49
	v_cvt_pk_bf16_f32 v107, v50, v51
	v_cvt_pk_bf16_f32 v108, v52, v53
	v_cvt_pk_bf16_f32 v109, v54, v55
	v_cvt_pk_bf16_f32 v110, v56, v57
	v_cvt_pk_bf16_f32 v111, v58, v59
	v_cvt_pk_bf16_f32 v112, v60, v61
	v_cvt_pk_bf16_f32 v113, v62, v63
	v_cvt_pk_bf16_f32 v114, v64, v65
	v_cvt_pk_bf16_f32 v115, v66, v67
	ds_write_b128 v2, v[100:103] offset:64
	ds_write_b128 v2, v[104:107] offset:80
	ds_write_b128 v2, v[108:111] offset:96
	ds_write_b128 v2, v[112:115] offset:112
	global_load_dword v36, v1, s[8:9]
	s_add_u32 s8, s8, s10
	s_addc_u32 s9, s9, 0
	global_load_dword v37, v1, s[8:9]
	s_add_u32 s8, s8, s10
	s_addc_u32 s9, s9, 0
	global_load_dword v38, v1, s[8:9]
	s_add_u32 s8, s8, s10
	s_addc_u32 s9, s9, 0
	global_load_dword v39, v1, s[8:9]
	s_add_u32 s8, s8, s10
	s_addc_u32 s9, s9, 0
	global_load_dword v40, v1, s[8:9]
	s_add_u32 s8, s8, s10
	s_addc_u32 s9, s9, 0
	global_load_dword v41, v1, s[8:9]
	s_add_u32 s8, s8, s10
	s_addc_u32 s9, s9, 0
	global_load_dword v42, v1, s[8:9]
	s_add_u32 s8, s8, s10
	s_addc_u32 s9, s9, 0
	global_load_dword v43, v1, s[8:9]
	s_add_u32 s8, s8, s10
	s_addc_u32 s9, s9, 0
	global_load_dword v44, v1, s[8:9]
	s_add_u32 s8, s8, s10
	s_addc_u32 s9, s9, 0
	global_load_dword v45, v1, s[8:9]
	s_add_u32 s8, s8, s10
	s_addc_u32 s9, s9, 0
	global_load_dword v46, v1, s[8:9]
	s_add_u32 s8, s8, s10
	s_addc_u32 s9, s9, 0
	global_load_dword v47, v1, s[8:9]
	s_add_u32 s8, s8, s10
	s_addc_u32 s9, s9, 0
	global_load_dword v48, v1, s[8:9]
	s_add_u32 s8, s8, s10
	s_addc_u32 s9, s9, 0
	global_load_dword v49, v1, s[8:9]
	s_add_u32 s8, s8, s10
	s_addc_u32 s9, s9, 0
	global_load_dword v50, v1, s[8:9]
	s_add_u32 s8, s8, s10
	s_addc_u32 s9, s9, 0
	global_load_dword v51, v1, s[8:9]
	s_add_u32 s8, s8, s10
	s_addc_u32 s9, s9, 0
	global_load_dword v52, v1, s[8:9]
	s_add_u32 s8, s8, s10
	s_addc_u32 s9, s9, 0
	global_load_dword v53, v1, s[8:9]
	s_add_u32 s8, s8, s10
	s_addc_u32 s9, s9, 0
	global_load_dword v54, v1, s[8:9]
	s_add_u32 s8, s8, s10
	s_addc_u32 s9, s9, 0
	global_load_dword v55, v1, s[8:9]
	s_add_u32 s8, s8, s10
	s_addc_u32 s9, s9, 0
	global_load_dword v56, v1, s[8:9]
	s_add_u32 s8, s8, s10
	s_addc_u32 s9, s9, 0
	global_load_dword v57, v1, s[8:9]
	s_add_u32 s8, s8, s10
	s_addc_u32 s9, s9, 0
	global_load_dword v58, v1, s[8:9]
	s_add_u32 s8, s8, s10
	s_addc_u32 s9, s9, 0
	global_load_dword v59, v1, s[8:9]
	s_add_u32 s8, s8, s10
	s_addc_u32 s9, s9, 0
	global_load_dword v60, v1, s[8:9]
	s_add_u32 s8, s8, s10
	s_addc_u32 s9, s9, 0
	global_load_dword v61, v1, s[8:9]
	s_add_u32 s8, s8, s10
	s_addc_u32 s9, s9, 0
	global_load_dword v62, v1, s[8:9]
	s_add_u32 s8, s8, s10
	s_addc_u32 s9, s9, 0
	global_load_dword v63, v1, s[8:9]
	s_add_u32 s8, s8, s10
	s_addc_u32 s9, s9, 0
	global_load_dword v64, v1, s[8:9]
	s_add_u32 s8, s8, s10
	s_addc_u32 s9, s9, 0
	global_load_dword v65, v1, s[8:9]
	s_add_u32 s8, s8, s10
	s_addc_u32 s9, s9, 0
	global_load_dword v66, v1, s[8:9]
	s_add_u32 s8, s8, s10
	s_addc_u32 s9, s9, 0
	global_load_dword v67, v1, s[8:9]
	s_add_u32 s8, s8, s10
	s_addc_u32 s9, s9, 0
	v_mov_b32_e32 v86, v84
	v_mov_b32_e32 v87, v85
	ds_read_b128 v[116:119], v3 offset:0
	ds_read_b128 v[120:123], v3 offset:1152
	ds_read_b128 v[124:127], v3 offset:2304
	ds_read_b128 v[128:131], v3 offset:3456
	s_waitcnt lgkmcnt(0)
; __device__ __forceinline__ void convert_item(const float* __restrict__ src, int Ksz, int Nsz, u16* __restrict__ dst, int kb, int nb,
;                                              int mode, const int tid) {
;     ...
; #pragma unroll
;     for (int q = 0; q < 8; ++q) {
;       u32x4 o;
;       o.x = pack2(v[q * 8 + 0], v[q * 8 + 1]);
;       o.y = pack2(v[q * 8 + 2], v[q * 8 + 3]);
;       o.z = pack2(v[q * 8 + 4], v[q * 8 + 5]);
;       o.w = pack2(v[q * 8 + 6], v[q * 8 + 7]);
;       d[q] = o;
;     }
	global_store_dwordx4 v[86:87], v[116:119], off offset:0
	v_lshl_add_u64 v[86:87], v[86:87], 0, s[6:7]
	global_store_dwordx4 v[86:87], v[120:123], off offset:0
	v_lshl_add_u64 v[86:87], v[86:87], 0, s[6:7]
	global_store_dwordx4 v[86:87], v[124:127], off offset:0
	v_lshl_add_u64 v[86:87], v[86:87], 0, s[6:7]
	global_store_dwordx4 v[86:87], v[128:131], off offset:0
	v_lshl_add_u64 v[86:87], v[86:87], 0, s[6:7]
	ds_read_b128 v[116:119], v3 offset:4608
	ds_read_b128 v[120:123], v3 offset:5760
	ds_read_b128 v[124:127], v3 offset:6912
	ds_read_b128 v[128:131], v3 offset:8064
	s_waitcnt lgkmcnt(0)
	global_store_dwordx4 v[86:87], v[116:119], off offset:0
	v_lshl_add_u64 v[86:87], v[86:87], 0, s[6:7]
	global_store_dwordx4 v[86:87], v[120:123], off offset:0
	v_lshl_add_u64 v[86:87], v[86:87], 0, s[6:7]
	global_store_dwordx4 v[86:87], v[124:127], off offset:0
	v_lshl_add_u64 v[86:87], v[86:87], 0, s[6:7]
	global_store_dwordx4 v[86:87], v[128:131], off offset:0
	v_lshl_add_u64 v[86:87], v[86:87], 0, s[6:7]
	s_waitcnt vmcnt(40)
	v_cvt_pk_bf16_f32 v68, v4, v5
	v_cvt_pk_bf16_f32 v69, v6, v7
	v_cvt_pk_bf16_f32 v70, v8, v9
	v_cvt_pk_bf16_f32 v71, v10, v11
	v_cvt_pk_bf16_f32 v72, v12, v13
	v_cvt_pk_bf16_f32 v73, v14, v15
	v_cvt_pk_bf16_f32 v74, v16, v17
	v_cvt_pk_bf16_f32 v75, v18, v19
	v_cvt_pk_bf16_f32 v76, v20, v21
	v_cvt_pk_bf16_f32 v77, v22, v23
	v_cvt_pk_bf16_f32 v78, v24, v25
	v_cvt_pk_bf16_f32 v79, v26, v27
	v_cvt_pk_bf16_f32 v80, v28, v29
	v_cvt_pk_bf16_f32 v81, v30, v31
	v_cvt_pk_bf16_f32 v82, v32, v33
	v_cvt_pk_bf16_f32 v83, v34, v35
	ds_write_b128 v2, v[68:71] offset:0
	ds_write_b128 v2, v[72:75] offset:16
	ds_write_b128 v2, v[76:79] offset:32
	ds_write_b128 v2, v[80:83] offset:48
	global_load_dword v4, v1, s[8:9]
	s_add_u32 s8, s8, s10
	s_addc_u32 s9, s9, 0
	global_load_dword v5, v1, s[8:9]
	s_add_u32 s8, s8, s10
	s_addc_u32 s9, s9, 0
	global_load_dword v6, v1, s[8:9]
	s_add_u32 s8, s8, s10
	s_addc_u32 s9, s9, 0
	global_load_dword v7, v1, s[8:9]
	s_add_u32 s8, s8, s10
	s_addc_u32 s9, s9, 0
	global_load_dword v8, v1, s[8:9]
	s_add_u32 s8, s8, s10
	s_addc_u32 s9, s9, 0
	global_load_dword v9, v1, s[8:9]
	s_add_u32 s8, s8, s10
	s_addc_u32 s9, s9, 0
	global_load_dword v10, v1, s[8:9]
	s_add_u32 s8, s8, s10
	s_addc_u32 s9, s9, 0
	global_load_dword v11, v1, s[8:9]
	s_add_u32 s8, s8, s10
	s_addc_u32 s9, s9, 0
	global_load_dword v12, v1, s[8:9]
	s_add_u32 s8, s8, s10
	s_addc_u32 s9, s9, 0
	global_load_dword v13, v1, s[8:9]
	s_add_u32 s8, s8, s10
	s_addc_u32 s9, s9, 0
	global_load_dword v14, v1, s[8:9]
	s_add_u32 s8, s8, s10
	s_addc_u32 s9, s9, 0
	global_load_dword v15, v1, s[8:9]
	s_add_u32 s8, s8, s10
	s_addc_u32 s9, s9, 0
	global_load_dword v16, v1, s[8:9]
	s_add_u32 s8, s8, s10
	s_addc_u32 s9, s9, 0
	global_load_dword v17, v1, s[8:9]
	s_add_u32 s8, s8, s10
	s_addc_u32 s9, s9, 0
	global_load_dword v18, v1, s[8:9]
	s_add_u32 s8, s8, s10
	s_addc_u32 s9, s9, 0
	global_load_dword v19, v1, s[8:9]
	s_add_u32 s8, s8, s10
	s_addc_u32 s9, s9, 0
	global_load_dword v20, v1, s[8:9]
	s_add_u32 s8, s8, s10
	s_addc_u32 s9, s9, 0
	global_load_dword v21, v1, s[8:9]
	s_add_u32 s8, s8, s10
	s_addc_u32 s9, s9, 0
	global_load_dword v22, v1, s[8:9]
	s_add_u32 s8, s8, s10
	s_addc_u32 s9, s9, 0
	global_load_dword v23, v1, s[8:9]
	s_add_u32 s8, s8, s10
	s_addc_u32 s9, s9, 0
	global_load_dword v24, v1, s[8:9]
	s_add_u32 s8, s8, s10
	s_addc_u32 s9, s9, 0
	global_load_dword v25, v1, s[8:9]
	s_add_u32 s8, s8, s10
	s_addc_u32 s9, s9, 0
	global_load_dword v26, v1, s[8:9]
	s_add_u32 s8, s8, s10
	s_addc_u32 s9, s9, 0
	global_load_dword v27, v1, s[8:9]
	s_add_u32 s8, s8, s10
	s_addc_u32 s9, s9, 0
	global_load_dword v28, v1, s[8:9]
	s_add_u32 s8, s8, s10
	s_addc_u32 s9, s9, 0
	global_load_dword v29, v1, s[8:9]
	s_add_u32 s8, s8, s10
	s_addc_u32 s9, s9, 0
	global_load_dword v30, v1, s[8:9]
	s_add_u32 s8, s8, s10
	s_addc_u32 s9, s9, 0
	global_load_dword v31, v1, s[8:9]
	s_add_u32 s8, s8, s10
	s_addc_u32 s9, s9, 0
	global_load_dword v32, v1, s[8:9]
	s_add_u32 s8, s8, s10
	s_addc_u32 s9, s9, 0
	global_load_dword v33, v1, s[8:9]
	s_add_u32 s8, s8, s10
	s_addc_u32 s9, s9, 0
	global_load_dword v34, v1, s[8:9]
	s_add_u32 s8, s8, s10
	s_addc_u32 s9, s9, 0
	global_load_dword v35, v1, s[8:9]
	s_add_u32 s8, s8, s10
	s_addc_u32 s9, s9, 0
	s_waitcnt vmcnt(40)
; __device__ __forceinline__ void convert_item(const float* __restrict__ src, int Ksz, int Nsz, u16* __restrict__ dst, int kb, int nb,
;                                              int mode, const int tid) {
;     ...
; #pragma unroll
;     for (int q = 0; q < 8; ++q) {
;       u32x4 o;
;       o.x = pack2(v[q * 8 + 0], v[q * 8 + 1]);
;       o.y = pack2(v[q * 8 + 2], v[q * 8 + 3]);
;       o.z = pack2(v[q * 8 + 4], v[q * 8 + 5]);
;       o.w = pack2(v[q * 8 + 6], v[q * 8 + 7]);
;       d[q] = o;
;     }
	v_cvt_pk_bf16_f32 v100, v36, v37
	v_cvt_pk_bf16_f32 v101, v38, v39
	v_cvt_pk_bf16_f32 v102, v40, v41
	v_cvt_pk_bf16_f32 v103, v42, v43
	v_cvt_pk_bf16_f32 v104, v44, v45
	v_cvt_pk_bf16_f32 v105, v46, v47
	v_cvt_pk_bf16_f32 v106, v48, v49
	v_cvt_pk_bf16_f32 v107, v50, v51
	v_cvt_pk_bf16_f32 v108, v52, v53
	v_cvt_pk_bf16_f32 v109, v54, v55
	v_cvt_pk_bf16_f32 v110, v56, v57
	v_cvt_pk_bf16_f32 v111, v58, v59
	v_cvt_pk_bf16_f32 v112, v60, v61
	v_cvt_pk_bf16_f32 v113, v62, v63
	v_cvt_pk_bf16_f32 v114, v64, v65
	v_cvt_pk_bf16_f32 v115, v66, v67
	ds_write_b128 v2, v[100:103] offset:64
	ds_write_b128 v2, v[104:107] offset:80
	ds_write_b128 v2, v[108:111] offset:96
	ds_write_b128 v2, v[112:115] offset:112
	global_load_dword v36, v1, s[8:9]
	s_add_u32 s8, s8, s10
	s_addc_u32 s9, s9, 0
	global_load_dword v37, v1, s[8:9]
	s_add_u32 s8, s8, s10
	s_addc_u32 s9, s9, 0
	global_load_dword v38, v1, s[8:9]
	s_add_u32 s8, s8, s10
	s_addc_u32 s9, s9, 0
	global_load_dword v39, v1, s[8:9]
	s_add_u32 s8, s8, s10
	s_addc_u32 s9, s9, 0
	global_load_dword v40, v1, s[8:9]
	s_add_u32 s8, s8, s10
	s_addc_u32 s9, s9, 0
	global_load_dword v41, v1, s[8:9]
	s_add_u32 s8, s8, s10
	s_addc_u32 s9, s9, 0
	global_load_dword v42, v1, s[8:9]
	s_add_u32 s8, s8, s10
	s_addc_u32 s9, s9, 0
	global_load_dword v43, v1, s[8:9]
	s_add_u32 s8, s8, s10
	s_addc_u32 s9, s9, 0
	global_load_dword v44, v1, s[8:9]
	s_add_u32 s8, s8, s10
	s_addc_u32 s9, s9, 0
	global_load_dword v45, v1, s[8:9]
	s_add_u32 s8, s8, s10
	s_addc_u32 s9, s9, 0
	global_load_dword v46, v1, s[8:9]
	s_add_u32 s8, s8, s10
	s_addc_u32 s9, s9, 0
	global_load_dword v47, v1, s[8:9]
	s_add_u32 s8, s8, s10
	s_addc_u32 s9, s9, 0
	global_load_dword v48, v1, s[8:9]
	s_add_u32 s8, s8, s10
	s_addc_u32 s9, s9, 0
	global_load_dword v49, v1, s[8:9]
	s_add_u32 s8, s8, s10
	s_addc_u32 s9, s9, 0
	global_load_dword v50, v1, s[8:9]
	s_add_u32 s8, s8, s10
	s_addc_u32 s9, s9, 0
	global_load_dword v51, v1, s[8:9]
	s_add_u32 s8, s8, s10
	s_addc_u32 s9, s9, 0
	global_load_dword v52, v1, s[8:9]
	s_add_u32 s8, s8, s10
	s_addc_u32 s9, s9, 0
	global_load_dword v53, v1, s[8:9]
	s_add_u32 s8, s8, s10
	s_addc_u32 s9, s9, 0
	global_load_dword v54, v1, s[8:9]
	s_add_u32 s8, s8, s10
	s_addc_u32 s9, s9, 0
	global_load_dword v55, v1, s[8:9]
	s_add_u32 s8, s8, s10
	s_addc_u32 s9, s9, 0
	global_load_dword v56, v1, s[8:9]
	s_add_u32 s8, s8, s10
	s_addc_u32 s9, s9, 0
	global_load_dword v57, v1, s[8:9]
	s_add_u32 s8, s8, s10
	s_addc_u32 s9, s9, 0
	global_load_dword v58, v1, s[8:9]
	s_add_u32 s8, s8, s10
	s_addc_u32 s9, s9, 0
	global_load_dword v59, v1, s[8:9]
	s_add_u32 s8, s8, s10
	s_addc_u32 s9, s9, 0
	global_load_dword v60, v1, s[8:9]
	s_add_u32 s8, s8, s10
	s_addc_u32 s9, s9, 0
	global_load_dword v61, v1, s[8:9]
	s_add_u32 s8, s8, s10
	s_addc_u32 s9, s9, 0
	global_load_dword v62, v1, s[8:9]
	s_add_u32 s8, s8, s10
	s_addc_u32 s9, s9, 0
	global_load_dword v63, v1, s[8:9]
	s_add_u32 s8, s8, s10
	s_addc_u32 s9, s9, 0
	global_load_dword v64, v1, s[8:9]
	s_add_u32 s8, s8, s10
	s_addc_u32 s9, s9, 0
	global_load_dword v65, v1, s[8:9]
	s_add_u32 s8, s8, s10
	s_addc_u32 s9, s9, 0
	global_load_dword v66, v1, s[8:9]
	s_add_u32 s8, s8, s10
	s_addc_u32 s9, s9, 0
	global_load_dword v67, v1, s[8:9]
	s_add_u32 s8, s8, s10
	s_addc_u32 s9, s9, 0
	v_mov_b32_e32 v86, v84
	v_mov_b32_e32 v87, v85
	ds_read_b128 v[116:119], v3 offset:0
	ds_read_b128 v[120:123], v3 offset:1152
	ds_read_b128 v[124:127], v3 offset:2304
	ds_read_b128 v[128:131], v3 offset:3456
	s_waitcnt lgkmcnt(0)
	global_store_dwordx4 v[86:87], v[116:119], off offset:128
	v_lshl_add_u64 v[86:87], v[86:87], 0, s[6:7]
	global_store_dwordx4 v[86:87], v[120:123], off offset:128
	v_lshl_add_u64 v[86:87], v[86:87], 0, s[6:7]
	global_store_dwordx4 v[86:87], v[124:127], off offset:128
	v_lshl_add_u64 v[86:87], v[86:87], 0, s[6:7]
	global_store_dwordx4 v[86:87], v[128:131], off offset:128
	v_lshl_add_u64 v[86:87], v[86:87], 0, s[6:7]
	ds_read_b128 v[116:119], v3 offset:4608
	ds_read_b128 v[120:123], v3 offset:5760
	ds_read_b128 v[124:127], v3 offset:6912
	ds_read_b128 v[128:131], v3 offset:8064
	s_waitcnt lgkmcnt(0)
	global_store_dwordx4 v[86:87], v[116:119], off offset:128
	v_lshl_add_u64 v[86:87], v[86:87], 0, s[6:7]
	global_store_dwordx4 v[86:87], v[120:123], off offset:128
	v_lshl_add_u64 v[86:87], v[86:87], 0, s[6:7]
	global_store_dwordx4 v[86:87], v[124:127], off offset:128
	v_lshl_add_u64 v[86:87], v[86:87], 0, s[6:7]
	global_store_dwordx4 v[86:87], v[128:131], off offset:128
	v_lshl_add_u64 v[86:87], v[86:87], 0, s[6:7]
	s_waitcnt vmcnt(40)
; __device__ __forceinline__ void convert_item(const float* __restrict__ src, int Ksz, int Nsz, u16* __restrict__ dst, int kb, int nb,
;                                              int mode, const int tid) {
;     ...
; #pragma unroll
;     for (int q = 0; q < 8; ++q) {
;       u32x4 o;
;       o.x = pack2(v[q * 8 + 0], v[q * 8 + 1]);
;       o.y = pack2(v[q * 8 + 2], v[q * 8 + 3]);
;       o.z = pack2(v[q * 8 + 4], v[q * 8 + 5]);
;       o.w = pack2(v[q * 8 + 6], v[q * 8 + 7]);
;       d[q] = o;
;     }
	v_cvt_pk_bf16_f32 v68, v4, v5
	v_cvt_pk_bf16_f32 v69, v6, v7
	v_cvt_pk_bf16_f32 v70, v8, v9
	v_cvt_pk_bf16_f32 v71, v10, v11
	v_cvt_pk_bf16_f32 v72, v12, v13
	v_cvt_pk_bf16_f32 v73, v14, v15
	v_cvt_pk_bf16_f32 v74, v16, v17
	v_cvt_pk_bf16_f32 v75, v18, v19
	v_cvt_pk_bf16_f32 v76, v20, v21
	v_cvt_pk_bf16_f32 v77, v22, v23
	v_cvt_pk_bf16_f32 v78, v24, v25
	v_cvt_pk_bf16_f32 v79, v26, v27
	v_cvt_pk_bf16_f32 v80, v28, v29
	v_cvt_pk_bf16_f32 v81, v30, v31
	v_cvt_pk_bf16_f32 v82, v32, v33
	v_cvt_pk_bf16_f32 v83, v34, v35
	ds_write_b128 v2, v[68:71] offset:0
	ds_write_b128 v2, v[72:75] offset:16
	ds_write_b128 v2, v[76:79] offset:32
	ds_write_b128 v2, v[80:83] offset:48
	global_load_dword v4, v1, s[8:9]
	s_add_u32 s8, s8, s10
	s_addc_u32 s9, s9, 0
	global_load_dword v5, v1, s[8:9]
	s_add_u32 s8, s8, s10
	s_addc_u32 s9, s9, 0
	global_load_dword v6, v1, s[8:9]
	s_add_u32 s8, s8, s10
	s_addc_u32 s9, s9, 0
	global_load_dword v7, v1, s[8:9]
	s_add_u32 s8, s8, s10
	s_addc_u32 s9, s9, 0
	global_load_dword v8, v1, s[8:9]
	s_add_u32 s8, s8, s10
	s_addc_u32 s9, s9, 0
	global_load_dword v9, v1, s[8:9]
	s_add_u32 s8, s8, s10
	s_addc_u32 s9, s9, 0
	global_load_dword v10, v1, s[8:9]
	s_add_u32 s8, s8, s10
	s_addc_u32 s9, s9, 0
	global_load_dword v11, v1, s[8:9]
	s_add_u32 s8, s8, s10
	s_addc_u32 s9, s9, 0
	global_load_dword v12, v1, s[8:9]
	s_add_u32 s8, s8, s10
	s_addc_u32 s9, s9, 0
	global_load_dword v13, v1, s[8:9]
	s_add_u32 s8, s8, s10
	s_addc_u32 s9, s9, 0
	global_load_dword v14, v1, s[8:9]
	s_add_u32 s8, s8, s10
	s_addc_u32 s9, s9, 0
	global_load_dword v15, v1, s[8:9]
	s_add_u32 s8, s8, s10
	s_addc_u32 s9, s9, 0
	global_load_dword v16, v1, s[8:9]
	s_add_u32 s8, s8, s10
	s_addc_u32 s9, s9, 0
	global_load_dword v17, v1, s[8:9]
	s_add_u32 s8, s8, s10
	s_addc_u32 s9, s9, 0
	global_load_dword v18, v1, s[8:9]
	s_add_u32 s8, s8, s10
	s_addc_u32 s9, s9, 0
	global_load_dword v19, v1, s[8:9]
	s_add_u32 s8, s8, s10
	s_addc_u32 s9, s9, 0
	global_load_dword v20, v1, s[8:9]
	s_add_u32 s8, s8, s10
	s_addc_u32 s9, s9, 0
	global_load_dword v21, v1, s[8:9]
	s_add_u32 s8, s8, s10
	s_addc_u32 s9, s9, 0
	global_load_dword v22, v1, s[8:9]
	s_add_u32 s8, s8, s10
	s_addc_u32 s9, s9, 0
	global_load_dword v23, v1, s[8:9]
	s_add_u32 s8, s8, s10
	s_addc_u32 s9, s9, 0
	global_load_dword v24, v1, s[8:9]
	s_add_u32 s8, s8, s10
	s_addc_u32 s9, s9, 0
	global_load_dword v25, v1, s[8:9]
	s_add_u32 s8, s8, s10
	s_addc_u32 s9, s9, 0
	global_load_dword v26, v1, s[8:9]
	s_add_u32 s8, s8, s10
	s_addc_u32 s9, s9, 0
	global_load_dword v27, v1, s[8:9]
	s_add_u32 s8, s8, s10
	s_addc_u32 s9, s9, 0
	global_load_dword v28, v1, s[8:9]
	s_add_u32 s8, s8, s10
	s_addc_u32 s9, s9, 0
	global_load_dword v29, v1, s[8:9]
	s_add_u32 s8, s8, s10
	s_addc_u32 s9, s9, 0
	global_load_dword v30, v1, s[8:9]
	s_add_u32 s8, s8, s10
	s_addc_u32 s9, s9, 0
	global_load_dword v31, v1, s[8:9]
	s_add_u32 s8, s8, s10
	s_addc_u32 s9, s9, 0
	global_load_dword v32, v1, s[8:9]
	s_add_u32 s8, s8, s10
	s_addc_u32 s9, s9, 0
	global_load_dword v33, v1, s[8:9]
	s_add_u32 s8, s8, s10
	s_addc_u32 s9, s9, 0
	global_load_dword v34, v1, s[8:9]
	s_add_u32 s8, s8, s10
	s_addc_u32 s9, s9, 0
	global_load_dword v35, v1, s[8:9]
	s_add_u32 s8, s8, s10
	s_addc_u32 s9, s9, 0
	s_waitcnt vmcnt(40)
	v_cvt_pk_bf16_f32 v100, v36, v37
	v_cvt_pk_bf16_f32 v101, v38, v39
	v_cvt_pk_bf16_f32 v102, v40, v41
	v_cvt_pk_bf16_f32 v103, v42, v43
	v_cvt_pk_bf16_f32 v104, v44, v45
	v_cvt_pk_bf16_f32 v105, v46, v47
	v_cvt_pk_bf16_f32 v106, v48, v49
	v_cvt_pk_bf16_f32 v107, v50, v51
	v_cvt_pk_bf16_f32 v108, v52, v53
	v_cvt_pk_bf16_f32 v109, v54, v55
	v_cvt_pk_bf16_f32 v110, v56, v57
	v_cvt_pk_bf16_f32 v111, v58, v59
	v_cvt_pk_bf16_f32 v112, v60, v61
	v_cvt_pk_bf16_f32 v113, v62, v63
	v_cvt_pk_bf16_f32 v114, v64, v65
	v_cvt_pk_bf16_f32 v115, v66, v67
	ds_write_b128 v2, v[100:103] offset:64
	ds_write_b128 v2, v[104:107] offset:80
	ds_write_b128 v2, v[108:111] offset:96
	ds_write_b128 v2, v[112:115] offset:112
	global_load_dword v36, v1, s[8:9]
	s_add_u32 s8, s8, s10
	s_addc_u32 s9, s9, 0
	global_load_dword v37, v1, s[8:9]
	s_add_u32 s8, s8, s10
	s_addc_u32 s9, s9, 0
	global_load_dword v38, v1, s[8:9]
	s_add_u32 s8, s8, s10
	s_addc_u32 s9, s9, 0
	global_load_dword v39, v1, s[8:9]
	s_add_u32 s8, s8, s10
	s_addc_u32 s9, s9, 0
	global_load_dword v40, v1, s[8:9]
	s_add_u32 s8, s8, s10
	s_addc_u32 s9, s9, 0
	global_load_dword v41, v1, s[8:9]
	s_add_u32 s8, s8, s10
	s_addc_u32 s9, s9, 0
	global_load_dword v42, v1, s[8:9]
	s_add_u32 s8, s8, s10
	s_addc_u32 s9, s9, 0
	global_load_dword v43, v1, s[8:9]
	s_add_u32 s8, s8, s10
	s_addc_u32 s9, s9, 0
	global_load_dword v44, v1, s[8:9]
	s_add_u32 s8, s8, s10
	s_addc_u32 s9, s9, 0
	global_load_dword v45, v1, s[8:9]
	s_add_u32 s8, s8, s10
	s_addc_u32 s9, s9, 0
	global_load_dword v46, v1, s[8:9]
	s_add_u32 s8, s8, s10
	s_addc_u32 s9, s9, 0
	global_load_dword v47, v1, s[8:9]
	s_add_u32 s8, s8, s10
	s_addc_u32 s9, s9, 0
	global_load_dword v48, v1, s[8:9]
	s_add_u32 s8, s8, s10
	s_addc_u32 s9, s9, 0
	global_load_dword v49, v1, s[8:9]
	s_add_u32 s8, s8, s10
	s_addc_u32 s9, s9, 0
	global_load_dword v50, v1, s[8:9]
	s_add_u32 s8, s8, s10
	s_addc_u32 s9, s9, 0
	global_load_dword v51, v1, s[8:9]
	s_add_u32 s8, s8, s10
	s_addc_u32 s9, s9, 0
	global_load_dword v52, v1, s[8:9]
	s_add_u32 s8, s8, s10
	s_addc_u32 s9, s9, 0
	global_load_dword v53, v1, s[8:9]
	s_add_u32 s8, s8, s10
	s_addc_u32 s9, s9, 0
	global_load_dword v54, v1, s[8:9]
	s_add_u32 s8, s8, s10
	s_addc_u32 s9, s9, 0
	global_load_dword v55, v1, s[8:9]
	s_add_u32 s8, s8, s10
	s_addc_u32 s9, s9, 0
	global_load_dword v56, v1, s[8:9]
	s_add_u32 s8, s8, s10
	s_addc_u32 s9, s9, 0
	global_load_dword v57, v1, s[8:9]
	s_add_u32 s8, s8, s10
	s_addc_u32 s9, s9, 0
	global_load_dword v58, v1, s[8:9]
	s_add_u32 s8, s8, s10
	s_addc_u32 s9, s9, 0
	global_load_dword v59, v1, s[8:9]
	s_add_u32 s8, s8, s10
	s_addc_u32 s9, s9, 0
	global_load_dword v60, v1, s[8:9]
	s_add_u32 s8, s8, s10
	s_addc_u32 s9, s9, 0
	global_load_dword v61, v1, s[8:9]
	s_add_u32 s8, s8, s10
	s_addc_u32 s9, s9, 0
	global_load_dword v62, v1, s[8:9]
	s_add_u32 s8, s8, s10
	s_addc_u32 s9, s9, 0
	global_load_dword v63, v1, s[8:9]
	s_add_u32 s8, s8, s10
	s_addc_u32 s9, s9, 0
	global_load_dword v64, v1, s[8:9]
	s_add_u32 s8, s8, s10
	s_addc_u32 s9, s9, 0
	global_load_dword v65, v1, s[8:9]
	s_add_u32 s8, s8, s10
	s_addc_u32 s9, s9, 0
	global_load_dword v66, v1, s[8:9]
	s_add_u32 s8, s8, s10
	s_addc_u32 s9, s9, 0
	global_load_dword v67, v1, s[8:9]
	s_add_u32 s8, s8, s10
	s_addc_u32 s9, s9, 0
	v_mov_b32_e32 v86, v84
	v_mov_b32_e32 v87, v85
	ds_read_b128 v[116:119], v3 offset:0
	ds_read_b128 v[120:123], v3 offset:1152
	ds_read_b128 v[124:127], v3 offset:2304
	ds_read_b128 v[128:131], v3 offset:3456
	s_waitcnt lgkmcnt(0)
; __device__ __forceinline__ void convert_item(const float* __restrict__ src, int Ksz, int Nsz, u16* __restrict__ dst, int kb, int nb,
;                                              int mode, const int tid) {
;     ...
; #pragma unroll
;     for (int q = 0; q < 8; ++q) {
;       u32x4 o;
;       o.x = pack2(v[q * 8 + 0], v[q * 8 + 1]);
;       o.y = pack2(v[q * 8 + 2], v[q * 8 + 3]);
;       o.z = pack2(v[q * 8 + 4], v[q * 8 + 5]);
;       o.w = pack2(v[q * 8 + 6], v[q * 8 + 7]);
;       d[q] = o;
;     }
	global_store_dwordx4 v[86:87], v[116:119], off offset:256
	v_lshl_add_u64 v[86:87], v[86:87], 0, s[6:7]
	global_store_dwordx4 v[86:87], v[120:123], off offset:256
	v_lshl_add_u64 v[86:87], v[86:87], 0, s[6:7]
	global_store_dwordx4 v[86:87], v[124:127], off offset:256
	v_lshl_add_u64 v[86:87], v[86:87], 0, s[6:7]
	global_store_dwordx4 v[86:87], v[128:131], off offset:256
	v_lshl_add_u64 v[86:87], v[86:87], 0, s[6:7]
	ds_read_b128 v[116:119], v3 offset:4608
	ds_read_b128 v[120:123], v3 offset:5760
	ds_read_b128 v[124:127], v3 offset:6912
	ds_read_b128 v[128:131], v3 offset:8064
	s_waitcnt lgkmcnt(0)
	global_store_dwordx4 v[86:87], v[116:119], off offset:256
	v_lshl_add_u64 v[86:87], v[86:87], 0, s[6:7]
	global_store_dwordx4 v[86:87], v[120:123], off offset:256
	v_lshl_add_u64 v[86:87], v[86:87], 0, s[6:7]
	global_store_dwordx4 v[86:87], v[124:127], off offset:256
	v_lshl_add_u64 v[86:87], v[86:87], 0, s[6:7]
	global_store_dwordx4 v[86:87], v[128:131], off offset:256
	v_lshl_add_u64 v[86:87], v[86:87], 0, s[6:7]
	s_waitcnt vmcnt(40)
	v_cvt_pk_bf16_f32 v68, v4, v5
	v_cvt_pk_bf16_f32 v69, v6, v7
	v_cvt_pk_bf16_f32 v70, v8, v9
	v_cvt_pk_bf16_f32 v71, v10, v11
	v_cvt_pk_bf16_f32 v72, v12, v13
	v_cvt_pk_bf16_f32 v73, v14, v15
	v_cvt_pk_bf16_f32 v74, v16, v17
	v_cvt_pk_bf16_f32 v75, v18, v19
	v_cvt_pk_bf16_f32 v76, v20, v21
	v_cvt_pk_bf16_f32 v77, v22, v23
	v_cvt_pk_bf16_f32 v78, v24, v25
	v_cvt_pk_bf16_f32 v79, v26, v27
	v_cvt_pk_bf16_f32 v80, v28, v29
	v_cvt_pk_bf16_f32 v81, v30, v31
	v_cvt_pk_bf16_f32 v82, v32, v33
	v_cvt_pk_bf16_f32 v83, v34, v35
	ds_write_b128 v2, v[68:71] offset:0
	ds_write_b128 v2, v[72:75] offset:16
	ds_write_b128 v2, v[76:79] offset:32
	ds_write_b128 v2, v[80:83] offset:48
	s_waitcnt vmcnt(8)
	v_cvt_pk_bf16_f32 v100, v36, v37
	v_cvt_pk_bf16_f32 v101, v38, v39
	v_cvt_pk_bf16_f32 v102, v40, v41
	v_cvt_pk_bf16_f32 v103, v42, v43
	v_cvt_pk_bf16_f32 v104, v44, v45
	v_cvt_pk_bf16_f32 v105, v46, v47
	v_cvt_pk_bf16_f32 v106, v48, v49
	v_cvt_pk_bf16_f32 v107, v50, v51
	v_cvt_pk_bf16_f32 v108, v52, v53
	v_cvt_pk_bf16_f32 v109, v54, v55
	v_cvt_pk_bf16_f32 v110, v56, v57
	v_cvt_pk_bf16_f32 v111, v58, v59
	v_cvt_pk_bf16_f32 v112, v60, v61
	v_cvt_pk_bf16_f32 v113, v62, v63
	v_cvt_pk_bf16_f32 v114, v64, v65
	v_cvt_pk_bf16_f32 v115, v66, v67
	ds_write_b128 v2, v[100:103] offset:64
	ds_write_b128 v2, v[104:107] offset:80
	ds_write_b128 v2, v[108:111] offset:96
	ds_write_b128 v2, v[112:115] offset:112
	v_mov_b32_e32 v86, v84
	v_mov_b32_e32 v87, v85
	ds_read_b128 v[116:119], v3 offset:0
	ds_read_b128 v[120:123], v3 offset:1152
	ds_read_b128 v[124:127], v3 offset:2304
	ds_read_b128 v[128:131], v3 offset:3456
	s_waitcnt lgkmcnt(0)
	global_store_dwordx4 v[86:87], v[116:119], off offset:384
	v_lshl_add_u64 v[86:87], v[86:87], 0, s[6:7]
	global_store_dwordx4 v[86:87], v[120:123], off offset:384
	v_lshl_add_u64 v[86:87], v[86:87], 0, s[6:7]
	global_store_dwordx4 v[86:87], v[124:127], off offset:384
	v_lshl_add_u64 v[86:87], v[86:87], 0, s[6:7]
	global_store_dwordx4 v[86:87], v[128:131], off offset:384
	v_lshl_add_u64 v[86:87], v[86:87], 0, s[6:7]
	ds_read_b128 v[116:119], v3 offset:4608
	ds_read_b128 v[120:123], v3 offset:5760
	ds_read_b128 v[124:127], v3 offset:6912
	ds_read_b128 v[128:131], v3 offset:8064
	s_waitcnt lgkmcnt(0)
	global_store_dwordx4 v[86:87], v[116:119], off offset:384
	v_lshl_add_u64 v[86:87], v[86:87], 0, s[6:7]
	global_store_dwordx4 v[86:87], v[120:123], off offset:384
	v_lshl_add_u64 v[86:87], v[86:87], 0, s[6:7]
	global_store_dwordx4 v[86:87], v[124:127], off offset:384
	v_lshl_add_u64 v[86:87], v[86:87], 0, s[6:7]
	global_store_dwordx4 v[86:87], v[128:131], off offset:384
	v_lshl_add_u64 v[86:87], v[86:87], 0, s[6:7]
